# P13 EpiFinal phase 2: final-gain quads loaded once (32 stores stream) + s_barrier before the tail path reuses the LDS row-scale table
# speedup vs baseline: 1.0011x; 1.0011x over previous
.LBB0_3496:
	s_or_b64 exec, exec, s[4:5]
	v_lshl_add_u64 v[132:133], v[132:133], 2, s[24:25]
	s_waitcnt lgkmcnt(0)
	s_barrier
	global_load_dwordx4 v[200:203], v[132:133], off
	global_load_dwordx4 v[204:207], v[132:133], off offset:16
	global_load_dwordx4 v[208:211], v[132:133], off offset:512
	global_load_dwordx4 v[212:215], v[132:133], off offset:528
	v_lshl_add_u32 v1, v1, 2, 0
	v_add_u32_e32 v1, 0x1000, v1
	ds_read2_b32 v[154:155], v1 offset1:16
	s_waitcnt lgkmcnt(0)
	v_pk_mul_f32 v[134:135], v[134:135], v[154:155] op_sel_hi:[1,0]
	v_pk_mul_f32 v[128:129], v[128:129], v[154:155] op_sel_hi:[1,0]
	s_waitcnt vmcnt(0)
	s_nop 1
	v_mov_b64_e32 v[150:151], v[200:201]
	v_mov_b64_e32 v[152:153], v[202:203]
	v_pk_mul_f32 v[150:151], v[150:151], v[134:135]
	v_pk_mul_f32 v[152:153], v[152:153], v[128:129]
	global_store_dwordx4 v[130:131], v[150:153], off
	v_pk_mul_f32 v[128:129], v[124:125], v[154:155] op_sel_hi:[1,0]
	v_pk_mul_f32 v[124:125], v[126:127], v[154:155] op_sel_hi:[1,0]
	s_nop 1
	v_mov_b64_e32 v[150:151], v[204:205]
	v_mov_b64_e32 v[152:153], v[206:207]
	v_pk_mul_f32 v[126:127], v[128:129], v[152:153]
	v_pk_mul_f32 v[124:125], v[124:125], v[150:151]
	global_store_dwordx4 v[130:131], v[124:127], off offset:16
	v_pk_mul_f32 v[128:129], v[120:121], v[154:155] op_sel_hi:[1,0]
	v_pk_mul_f32 v[120:121], v[122:123], v[154:155] op_sel_hi:[1,0]
	s_nop 1
	v_mov_b64_e32 v[124:125], v[208:209]
	v_mov_b64_e32 v[126:127], v[210:211]
	v_pk_mul_f32 v[122:123], v[128:129], v[126:127]
	v_pk_mul_f32 v[120:121], v[120:121], v[124:125]
	global_store_dwordx4 v[130:131], v[120:123], off offset:512
	v_pk_mul_f32 v[124:125], v[116:117], v[154:155] op_sel_hi:[1,0]
	v_pk_mul_f32 v[116:117], v[118:119], v[154:155] op_sel_hi:[1,0]
	s_nop 1
	v_mov_b64_e32 v[120:121], v[212:213]
	v_mov_b64_e32 v[122:123], v[214:215]
	v_pk_mul_f32 v[118:119], v[124:125], v[122:123]
	v_pk_mul_f32 v[116:117], v[116:117], v[120:121]
	global_store_dwordx4 v[130:131], v[116:119], off offset:528
	v_mov_b32_e32 v120, v155
	v_pk_mul_f32 v[112:113], v[112:113], v[120:121] op_sel_hi:[1,0]
	v_pk_mul_f32 v[122:123], v[136:137], v[120:121] op_sel_hi:[1,0]
	s_nop 1
	v_mov_b64_e32 v[116:117], v[200:201]
	v_mov_b64_e32 v[118:119], v[202:203]
	v_pk_mul_f32 v[118:119], v[118:119], v[112:113]
	v_pk_mul_f32 v[116:117], v[116:117], v[122:123]
	global_store_dwordx4 v[114:115], v[116:119], off
	v_pk_mul_f32 v[112:113], v[108:109], v[120:121] op_sel_hi:[1,0]
	v_pk_mul_f32 v[108:109], v[110:111], v[120:121] op_sel_hi:[1,0]
	s_nop 1
	v_mov_b64_e32 v[116:117], v[204:205]
	v_mov_b64_e32 v[118:119], v[206:207]
	v_pk_mul_f32 v[110:111], v[112:113], v[118:119]
	v_pk_mul_f32 v[108:109], v[108:109], v[116:117]
	global_store_dwordx4 v[114:115], v[108:111], off offset:16
	v_pk_mul_f32 v[112:113], v[104:105], v[120:121] op_sel_hi:[1,0]
	v_pk_mul_f32 v[104:105], v[106:107], v[120:121] op_sel_hi:[1,0]
	s_nop 1
	v_mov_b64_e32 v[108:109], v[208:209]
	v_mov_b64_e32 v[110:111], v[210:211]
	v_pk_mul_f32 v[106:107], v[112:113], v[110:111]
	v_pk_mul_f32 v[104:105], v[104:105], v[108:109]
	global_store_dwordx4 v[114:115], v[104:107], off offset:512
	v_pk_mul_f32 v[108:109], v[100:101], v[120:121] op_sel_hi:[1,0]
	v_pk_mul_f32 v[100:101], v[102:103], v[120:121] op_sel_hi:[1,0]
	s_nop 1
	v_mov_b64_e32 v[104:105], v[212:213]
	v_mov_b64_e32 v[106:107], v[214:215]
	v_pk_mul_f32 v[102:103], v[108:109], v[106:107]
	v_pk_mul_f32 v[100:101], v[100:101], v[104:105]
	global_store_dwordx4 v[114:115], v[100:103], off offset:528
	ds_read2_b32 v[104:105], v1 offset0:32 offset1:48
	s_waitcnt lgkmcnt(0)
	v_pk_mul_f32 v[106:107], v[138:139], v[104:105] op_sel_hi:[1,0]
	v_pk_mul_f32 v[96:97], v[96:97], v[104:105] op_sel_hi:[1,0]
	s_nop 1
	v_mov_b64_e32 v[100:101], v[200:201]
	v_mov_b64_e32 v[102:103], v[202:203]
	v_pk_mul_f32 v[100:101], v[100:101], v[106:107]
	v_pk_mul_f32 v[102:103], v[102:103], v[96:97]
	global_store_dwordx4 v[98:99], v[100:103], off
	v_pk_mul_f32 v[96:97], v[92:93], v[104:105] op_sel_hi:[1,0]
	v_pk_mul_f32 v[92:93], v[94:95], v[104:105] op_sel_hi:[1,0]
	s_nop 1
	v_mov_b64_e32 v[100:101], v[204:205]
	v_mov_b64_e32 v[102:103], v[206:207]
	v_pk_mul_f32 v[94:95], v[96:97], v[102:103]
	v_pk_mul_f32 v[92:93], v[92:93], v[100:101]
	global_store_dwordx4 v[98:99], v[92:95], off offset:16
	v_pk_mul_f32 v[96:97], v[88:89], v[104:105] op_sel_hi:[1,0]
	v_pk_mul_f32 v[88:89], v[90:91], v[104:105] op_sel_hi:[1,0]
	s_nop 1
	v_mov_b64_e32 v[92:93], v[208:209]
	v_mov_b64_e32 v[94:95], v[210:211]
	v_pk_mul_f32 v[90:91], v[96:97], v[94:95]
	v_pk_mul_f32 v[88:89], v[88:89], v[92:93]
	global_store_dwordx4 v[98:99], v[88:91], off offset:512
	v_pk_mul_f32 v[92:93], v[84:85], v[104:105] op_sel_hi:[1,0]
	v_pk_mul_f32 v[84:85], v[86:87], v[104:105] op_sel_hi:[1,0]
	s_nop 1
	v_mov_b64_e32 v[88:89], v[212:213]
	v_mov_b64_e32 v[90:91], v[214:215]
	v_pk_mul_f32 v[86:87], v[92:93], v[90:91]
	v_pk_mul_f32 v[84:85], v[84:85], v[88:89]
	global_store_dwordx4 v[98:99], v[84:87], off offset:528
	v_mov_b32_e32 v88, v105
	v_pk_mul_f32 v[90:91], v[142:143], v[88:89] op_sel_hi:[1,0]
	v_pk_mul_f32 v[80:81], v[80:81], v[88:89] op_sel_hi:[1,0]
	s_nop 1
	v_mov_b64_e32 v[84:85], v[200:201]
	v_mov_b64_e32 v[86:87], v[202:203]
	v_pk_mul_f32 v[84:85], v[84:85], v[90:91]
	v_pk_mul_f32 v[86:87], v[86:87], v[80:81]
	global_store_dwordx4 v[82:83], v[84:87], off
	v_pk_mul_f32 v[80:81], v[76:77], v[88:89] op_sel_hi:[1,0]
	v_pk_mul_f32 v[76:77], v[78:79], v[88:89] op_sel_hi:[1,0]
	s_nop 1
	v_mov_b64_e32 v[84:85], v[204:205]
	v_mov_b64_e32 v[86:87], v[206:207]
	v_pk_mul_f32 v[78:79], v[80:81], v[86:87]
	v_pk_mul_f32 v[76:77], v[76:77], v[84:85]
	global_store_dwordx4 v[82:83], v[76:79], off offset:16
	v_pk_mul_f32 v[80:81], v[72:73], v[88:89] op_sel_hi:[1,0]
	v_pk_mul_f32 v[72:73], v[74:75], v[88:89] op_sel_hi:[1,0]
	s_nop 1
	v_mov_b64_e32 v[76:77], v[208:209]
	v_mov_b64_e32 v[78:79], v[210:211]
	v_pk_mul_f32 v[74:75], v[80:81], v[78:79]
	v_pk_mul_f32 v[72:73], v[72:73], v[76:77]
	global_store_dwordx4 v[82:83], v[72:75], off offset:512
	v_pk_mul_f32 v[76:77], v[68:69], v[88:89] op_sel_hi:[1,0]
	v_pk_mul_f32 v[68:69], v[70:71], v[88:89] op_sel_hi:[1,0]
	s_nop 1
	v_mov_b64_e32 v[72:73], v[212:213]
	v_mov_b64_e32 v[74:75], v[214:215]
	v_pk_mul_f32 v[70:71], v[76:77], v[74:75]
	v_pk_mul_f32 v[68:69], v[68:69], v[72:73]
	global_store_dwordx4 v[82:83], v[68:71], off offset:528
	ds_read2_b32 v[72:73], v1 offset0:128 offset1:144
	s_waitcnt lgkmcnt(0)
	v_pk_mul_f32 v[74:75], v[144:145], v[72:73] op_sel_hi:[1,0]
	v_pk_mul_f32 v[64:65], v[64:65], v[72:73] op_sel_hi:[1,0]
	s_nop 1
	v_mov_b64_e32 v[68:69], v[200:201]
	v_mov_b64_e32 v[70:71], v[202:203]
	v_pk_mul_f32 v[68:69], v[68:69], v[74:75]
	v_pk_mul_f32 v[70:71], v[70:71], v[64:65]
	global_store_dwordx4 v[66:67], v[68:71], off
	v_pk_mul_f32 v[64:65], v[60:61], v[72:73] op_sel_hi:[1,0]
	v_pk_mul_f32 v[60:61], v[62:63], v[72:73] op_sel_hi:[1,0]
	s_nop 1
	v_mov_b64_e32 v[68:69], v[204:205]
	v_mov_b64_e32 v[70:71], v[206:207]
	v_pk_mul_f32 v[62:63], v[64:65], v[70:71]
	v_pk_mul_f32 v[60:61], v[60:61], v[68:69]
	global_store_dwordx4 v[66:67], v[60:63], off offset:16
	v_pk_mul_f32 v[64:65], v[56:57], v[72:73] op_sel_hi:[1,0]
	v_pk_mul_f32 v[56:57], v[58:59], v[72:73] op_sel_hi:[1,0]
	s_nop 1
	v_mov_b64_e32 v[60:61], v[208:209]
	v_mov_b64_e32 v[62:63], v[210:211]
	v_pk_mul_f32 v[58:59], v[64:65], v[62:63]
	v_pk_mul_f32 v[56:57], v[56:57], v[60:61]
	global_store_dwordx4 v[66:67], v[56:59], off offset:512
	v_pk_mul_f32 v[60:61], v[52:53], v[72:73] op_sel_hi:[1,0]
	v_pk_mul_f32 v[52:53], v[54:55], v[72:73] op_sel_hi:[1,0]
	s_nop 1
	v_mov_b64_e32 v[56:57], v[212:213]
	v_mov_b64_e32 v[58:59], v[214:215]
	v_pk_mul_f32 v[54:55], v[60:61], v[58:59]
	v_pk_mul_f32 v[52:53], v[52:53], v[56:57]
	global_store_dwordx4 v[66:67], v[52:55], off offset:528
	v_mov_b32_e32 v56, v73
	v_pk_mul_f32 v[58:59], v[146:147], v[56:57] op_sel_hi:[1,0]
	v_pk_mul_f32 v[48:49], v[48:49], v[56:57] op_sel_hi:[1,0]
	s_nop 1
	v_mov_b64_e32 v[52:53], v[200:201]
	v_mov_b64_e32 v[54:55], v[202:203]
	v_pk_mul_f32 v[52:53], v[52:53], v[58:59]
	v_pk_mul_f32 v[54:55], v[54:55], v[48:49]
	global_store_dwordx4 v[50:51], v[52:55], off
	v_pk_mul_f32 v[48:49], v[44:45], v[56:57] op_sel_hi:[1,0]
	v_pk_mul_f32 v[44:45], v[46:47], v[56:57] op_sel_hi:[1,0]
	s_nop 1
	v_mov_b64_e32 v[52:53], v[204:205]
	v_mov_b64_e32 v[54:55], v[206:207]
	v_pk_mul_f32 v[46:47], v[48:49], v[54:55]
	v_pk_mul_f32 v[44:45], v[44:45], v[52:53]
	global_store_dwordx4 v[50:51], v[44:47], off offset:16
	v_pk_mul_f32 v[48:49], v[40:41], v[56:57] op_sel_hi:[1,0]
	v_pk_mul_f32 v[40:41], v[42:43], v[56:57] op_sel_hi:[1,0]
	s_nop 1
	v_mov_b64_e32 v[44:45], v[208:209]
	v_mov_b64_e32 v[46:47], v[210:211]
	v_pk_mul_f32 v[42:43], v[48:49], v[46:47]
	v_pk_mul_f32 v[40:41], v[40:41], v[44:45]
	global_store_dwordx4 v[50:51], v[40:43], off offset:512
	v_pk_mul_f32 v[44:45], v[36:37], v[56:57] op_sel_hi:[1,0]
	v_pk_mul_f32 v[36:37], v[38:39], v[56:57] op_sel_hi:[1,0]
	s_nop 1
	v_mov_b64_e32 v[40:41], v[212:213]
	v_mov_b64_e32 v[42:43], v[214:215]
	v_pk_mul_f32 v[38:39], v[44:45], v[42:43]
	v_pk_mul_f32 v[36:37], v[36:37], v[40:41]
	global_store_dwordx4 v[50:51], v[36:39], off offset:528
	ds_read2_b32 v[40:41], v1 offset0:160 offset1:176
	s_waitcnt lgkmcnt(0)
	v_pk_mul_f32 v[42:43], v[148:149], v[40:41] op_sel_hi:[1,0]
	v_pk_mul_f32 v[32:33], v[32:33], v[40:41] op_sel_hi:[1,0]
	s_nop 1
	v_mov_b64_e32 v[36:37], v[200:201]
	v_mov_b64_e32 v[38:39], v[202:203]
	v_pk_mul_f32 v[36:37], v[36:37], v[42:43]
	v_pk_mul_f32 v[38:39], v[38:39], v[32:33]
	global_store_dwordx4 v[34:35], v[36:39], off
	v_pk_mul_f32 v[32:33], v[28:29], v[40:41] op_sel_hi:[1,0]
	v_pk_mul_f32 v[28:29], v[30:31], v[40:41] op_sel_hi:[1,0]
	s_nop 1
	v_mov_b64_e32 v[36:37], v[204:205]
	v_mov_b64_e32 v[38:39], v[206:207]
	v_pk_mul_f32 v[30:31], v[32:33], v[38:39]
	v_pk_mul_f32 v[28:29], v[28:29], v[36:37]
	global_store_dwordx4 v[34:35], v[28:31], off offset:16
	v_pk_mul_f32 v[32:33], v[24:25], v[40:41] op_sel_hi:[1,0]
	v_pk_mul_f32 v[24:25], v[26:27], v[40:41] op_sel_hi:[1,0]
	s_nop 1
	v_mov_b64_e32 v[28:29], v[208:209]
	v_mov_b64_e32 v[30:31], v[210:211]
	v_pk_mul_f32 v[26:27], v[32:33], v[30:31]
	v_pk_mul_f32 v[24:25], v[24:25], v[28:29]
	global_store_dwordx4 v[34:35], v[24:27], off offset:512
	v_pk_mul_f32 v[28:29], v[20:21], v[40:41] op_sel_hi:[1,0]
	v_pk_mul_f32 v[20:21], v[22:23], v[40:41] op_sel_hi:[1,0]
	s_nop 1
	v_mov_b64_e32 v[24:25], v[212:213]
	v_mov_b64_e32 v[26:27], v[214:215]
	v_pk_mul_f32 v[22:23], v[28:29], v[26:27]
	v_pk_mul_f32 v[20:21], v[20:21], v[24:25]
	global_store_dwordx4 v[34:35], v[20:23], off offset:528
	v_mov_b32_e32 v24, v41
	v_pk_mul_f32 v[14:15], v[14:15], v[24:25] op_sel_hi:[1,0]
	v_pk_mul_f32 v[16:17], v[16:17], v[24:25] op_sel_hi:[1,0]
	v_pk_mul_f32 v[12:13], v[12:13], v[24:25] op_sel_hi:[1,0]
	v_pk_mul_f32 v[10:11], v[10:11], v[24:25] op_sel_hi:[1,0]
	v_pk_mul_f32 v[8:9], v[8:9], v[24:25] op_sel_hi:[1,0]
	v_pk_mul_f32 v[6:7], v[6:7], v[24:25] op_sel_hi:[1,0]
	v_pk_mul_f32 v[4:5], v[4:5], v[24:25] op_sel_hi:[1,0]
	v_pk_mul_f32 v[2:3], v[2:3], v[24:25] op_sel_hi:[1,0]
	s_nop 1
	v_mov_b64_e32 v[20:21], v[200:201]
	v_mov_b64_e32 v[22:23], v[202:203]
	v_pk_mul_f32 v[16:17], v[22:23], v[16:17]
	v_pk_mul_f32 v[14:15], v[20:21], v[14:15]
	global_store_dwordx4 v[18:19], v[14:17], off
	s_nop 1
	v_mov_b64_e32 v[14:15], v[204:205]
	v_mov_b64_e32 v[16:17], v[206:207]
	v_pk_mul_f32 v[10:11], v[10:11], v[14:15]
	v_pk_mul_f32 v[12:13], v[12:13], v[16:17]
	global_store_dwordx4 v[18:19], v[10:13], off offset:16
	s_nop 1
	v_mov_b64_e32 v[10:11], v[208:209]
	v_mov_b64_e32 v[12:13], v[210:211]
	v_pk_mul_f32 v[6:7], v[6:7], v[10:11]
	v_pk_mul_f32 v[8:9], v[8:9], v[12:13]
	global_store_dwordx4 v[18:19], v[6:9], off offset:512
	s_nop 1
	v_mov_b64_e32 v[6:7], v[212:213]
	v_mov_b64_e32 v[8:9], v[214:215]
	v_pk_mul_f32 v[2:3], v[2:3], v[6:7]
	v_pk_mul_f32 v[4:5], v[4:5], v[8:9]
	global_store_dwordx4 v[18:19], v[2:5], off offset:528
	s_barrier
